# v6 plus attention step: issue the 4 K-fragment ds_reads of a QK tile and the 8 V-fragment ds_reads of a PV block up front into spare VGPRs, counted lgkmcnt
# speedup vs baseline: 1.0198x; 1.0035x over previous
.LBB0_498:
	s_ashr_i32 s12, s10, 31
	s_and_b32 s31, s12, s57
	s_and_b64 s[12:13], exec, s[42:43]
	s_cselect_b32 s54, s57, 7
	s_cmp_gt_i32 s31, 0
	s_cselect_b64 s[12:13], -1, 0
	s_cmp_lt_i32 s54, 0
	s_cselect_b64 s[80:81], -1, 0
	v_add_u32_e32 v98, s44, v132
	s_or_b64 s[40:41], s[12:13], s[80:81]
	v_mov_b32_e32 v122, 0
	s_and_b64 vcc, exec, s[40:41]
	v_add_u32_e32 v137, v98, v141
	v_mov_b32_e32 v126, 0
	v_mov_b32_e32 v127, 0
	v_mov_b32_e32 v128, 0
	v_mov_b32_e32 v129, 0
	s_cbranch_vccnz .LBB0_500
	ds_read_b128 v[98:101], v137
	ds_read_b128 v[102:105], v137 offset:64
	ds_read_b128 v[184:187], v137 offset:128
	ds_read_b128 v[152:155], v137 offset:192
	s_waitcnt lgkmcnt(3)
	v_mfma_f32_16x16x32_bf16 v[98:101], v[98:101], v[94:97], 0
	s_waitcnt lgkmcnt(2)
	v_mfma_f32_16x16x32_bf16 v[98:101], v[102:105], v[90:93], v[98:101]
	s_waitcnt lgkmcnt(1)
	v_mfma_f32_16x16x32_bf16 v[98:101], v[184:187], v[86:89], v[98:101]
	s_waitcnt lgkmcnt(0)
	v_mfma_f32_16x16x32_bf16 v[126:129], v[152:155], v[82:85], v[98:101]
.LBB0_500:
	s_cmp_gt_i32 s31, 1
	s_cselect_b64 s[86:87], -1, 0
	s_cmp_lt_i32 s54, 1
	s_cselect_b64 s[12:13], -1, 0
	s_or_b64 s[42:43], s[86:87], s[12:13]
	s_and_b64 vcc, exec, s[42:43]
	v_mov_b32_e32 v123, 0
	v_mov_b32_e32 v124, 0
	v_mov_b32_e32 v125, 0
	s_cbranch_vccnz .LBB0_502
	ds_read_b128 v[98:101], v137 offset:4352
	ds_read_b128 v[102:105], v137 offset:4416
	ds_read_b128 v[184:187], v137 offset:4480
	ds_read_b128 v[152:155], v137 offset:4544
	s_waitcnt lgkmcnt(3)
	v_mfma_f32_16x16x32_bf16 v[98:101], v[98:101], v[94:97], 0
	s_waitcnt lgkmcnt(2)
	v_mfma_f32_16x16x32_bf16 v[98:101], v[102:105], v[90:93], v[98:101]
	s_waitcnt lgkmcnt(1)
	v_mfma_f32_16x16x32_bf16 v[98:101], v[184:187], v[86:89], v[98:101]
	s_waitcnt lgkmcnt(0)
	v_mfma_f32_16x16x32_bf16 v[122:125], v[152:155], v[82:85], v[98:101]
.LBB0_502:
	s_cmp_gt_i32 s31, 2
	s_cselect_b64 s[12:13], -1, 0
	s_cmp_lt_i32 s54, 2
	s_cselect_b64 s[76:77], -1, 0
	s_or_b64 s[44:45], s[12:13], s[76:77]
	v_mov_b32_e32 v114, 0
	s_and_b64 vcc, exec, s[44:45]
	v_mov_b32_e32 v118, 0
	v_mov_b32_e32 v119, 0
	v_mov_b32_e32 v120, 0
	v_mov_b32_e32 v121, 0
	s_cbranch_vccnz .LBB0_504
	ds_read_b128 v[98:101], v137 offset:8704
	ds_read_b128 v[102:105], v137 offset:8768
	ds_read_b128 v[184:187], v137 offset:8832
	ds_read_b128 v[152:155], v137 offset:8896
	s_waitcnt lgkmcnt(3)
	v_mfma_f32_16x16x32_bf16 v[98:101], v[98:101], v[94:97], 0
	s_waitcnt lgkmcnt(2)
	v_mfma_f32_16x16x32_bf16 v[98:101], v[102:105], v[90:93], v[98:101]
	s_waitcnt lgkmcnt(1)
	v_mfma_f32_16x16x32_bf16 v[98:101], v[184:187], v[86:89], v[98:101]
	s_waitcnt lgkmcnt(0)
	v_mfma_f32_16x16x32_bf16 v[118:121], v[152:155], v[82:85], v[98:101]
.LBB0_504:
	s_cmp_gt_i32 s31, 3
	s_cselect_b64 s[84:85], -1, 0
	s_cmp_lt_i32 s54, 3
	s_cselect_b64 s[12:13], -1, 0
	s_or_b64 s[46:47], s[84:85], s[12:13]
	s_and_b64 vcc, exec, s[46:47]
	v_mov_b32_e32 v115, 0
	v_mov_b32_e32 v116, 0
	v_mov_b32_e32 v117, 0
	s_cbranch_vccnz .LBB0_506
	ds_read_b128 v[98:101], v137 offset:13056
	ds_read_b128 v[102:105], v137 offset:13120
	ds_read_b128 v[184:187], v137 offset:13184
	ds_read_b128 v[152:155], v137 offset:13248
	s_waitcnt lgkmcnt(3)
	v_mfma_f32_16x16x32_bf16 v[98:101], v[98:101], v[94:97], 0
	s_waitcnt lgkmcnt(2)
	v_mfma_f32_16x16x32_bf16 v[98:101], v[102:105], v[90:93], v[98:101]
	s_waitcnt lgkmcnt(1)
	v_mfma_f32_16x16x32_bf16 v[98:101], v[184:187], v[86:89], v[98:101]
	s_waitcnt lgkmcnt(0)
	v_mfma_f32_16x16x32_bf16 v[114:117], v[152:155], v[82:85], v[98:101]
.LBB0_506:
	s_cmp_gt_i32 s31, 4
	s_cselect_b64 s[12:13], -1, 0
	s_cmp_lt_i32 s54, 4
	s_cselect_b64 s[74:75], -1, 0
	s_or_b64 s[48:49], s[12:13], s[74:75]
	v_mov_b32_e32 v106, 0
	s_and_b64 vcc, exec, s[48:49]
	v_mov_b32_e32 v110, 0
	v_mov_b32_e32 v111, 0
	v_mov_b32_e32 v112, 0
	v_mov_b32_e32 v113, 0
	s_cbranch_vccnz .LBB0_508
	ds_read_b128 v[98:101], v137 offset:17408
	ds_read_b128 v[102:105], v137 offset:17472
	ds_read_b128 v[184:187], v137 offset:17536
	ds_read_b128 v[152:155], v137 offset:17600
	s_waitcnt lgkmcnt(3)
	v_mfma_f32_16x16x32_bf16 v[98:101], v[98:101], v[94:97], 0
	s_waitcnt lgkmcnt(2)
	v_mfma_f32_16x16x32_bf16 v[98:101], v[102:105], v[90:93], v[98:101]
	s_waitcnt lgkmcnt(1)
	v_mfma_f32_16x16x32_bf16 v[98:101], v[184:187], v[86:89], v[98:101]
	s_waitcnt lgkmcnt(0)
	v_mfma_f32_16x16x32_bf16 v[110:113], v[152:155], v[82:85], v[98:101]
.LBB0_508:
	s_cmp_gt_i32 s31, 5
	s_cselect_b64 s[82:83], -1, 0
	s_cmp_lt_i32 s54, 5
	s_cselect_b64 s[12:13], -1, 0
	s_or_b64 s[50:51], s[82:83], s[12:13]
	s_and_b64 vcc, exec, s[50:51]
	v_mov_b32_e32 v107, 0
	v_mov_b32_e32 v108, 0
	v_mov_b32_e32 v109, 0
	s_cbranch_vccnz .LBB0_510
	ds_read_b128 v[98:101], v137 offset:21760
	ds_read_b128 v[102:105], v137 offset:21824
	ds_read_b128 v[184:187], v137 offset:21888
	ds_read_b128 v[152:155], v137 offset:21952
	s_waitcnt lgkmcnt(3)
	v_mfma_f32_16x16x32_bf16 v[98:101], v[98:101], v[94:97], 0
	s_waitcnt lgkmcnt(2)
	v_mfma_f32_16x16x32_bf16 v[98:101], v[102:105], v[90:93], v[98:101]
	s_waitcnt lgkmcnt(1)
	v_mfma_f32_16x16x32_bf16 v[98:101], v[184:187], v[86:89], v[98:101]
	s_waitcnt lgkmcnt(0)
	v_mfma_f32_16x16x32_bf16 v[106:109], v[152:155], v[82:85], v[98:101]
.LBB0_510:
	s_cmp_gt_i32 s31, 6
	s_cselect_b64 s[12:13], -1, 0
	s_cmp_lt_i32 s54, 6
	s_cselect_b64 s[72:73], -1, 0
	s_or_b64 s[52:53], s[12:13], s[72:73]
	v_mov_b32_e32 v98, 0
	s_and_b64 vcc, exec, s[52:53]
	v_mov_b32_e32 v102, 0
	v_mov_b32_e32 v103, 0
	v_mov_b32_e32 v104, 0
	v_mov_b32_e32 v105, 0
	s_cbranch_vccnz .LBB0_512
	ds_read_b128 v[100:103], v137 offset:26112
	ds_read_b128 v[144:147], v137 offset:26176
	ds_read_b128 v[184:187], v137 offset:26240
	ds_read_b128 v[152:155], v137 offset:26304
	s_waitcnt lgkmcnt(3)
	v_mfma_f32_16x16x32_bf16 v[100:103], v[100:103], v[94:97], 0
	s_waitcnt lgkmcnt(2)
	v_mfma_f32_16x16x32_bf16 v[100:103], v[144:147], v[90:93], v[100:103]
	s_waitcnt lgkmcnt(1)
	v_mfma_f32_16x16x32_bf16 v[100:103], v[184:187], v[86:89], v[100:103]
	s_waitcnt lgkmcnt(0)
	v_mfma_f32_16x16x32_bf16 v[102:105], v[152:155], v[82:85], v[100:103]
.LBB0_512:
	s_cmp_gt_i32 s31, 7
	s_cselect_b64 s[78:79], -1, 0
	s_cmp_lt_i32 s54, 7
	s_cselect_b64 s[12:13], -1, 0
	s_or_b64 s[54:55], s[78:79], s[12:13]
	s_and_b64 vcc, exec, s[54:55]
	v_mov_b32_e32 v99, 0
	v_mov_b32_e32 v100, 0
	v_mov_b32_e32 v101, 0
	s_cbranch_vccnz .LBB0_514
	ds_read_b128 v[98:101], v137 offset:30464
	ds_read_b128 v[144:147], v137 offset:30528
	ds_read_b128 v[184:187], v137 offset:30592
	ds_read_b128 v[152:155], v137 offset:30656
	s_waitcnt lgkmcnt(3)
	v_mfma_f32_16x16x32_bf16 v[98:101], v[98:101], v[94:97], 0
	s_waitcnt lgkmcnt(2)
	v_mfma_f32_16x16x32_bf16 v[98:101], v[144:147], v[90:93], v[98:101]
	s_waitcnt lgkmcnt(1)
	v_mfma_f32_16x16x32_bf16 v[98:101], v[184:187], v[86:89], v[98:101]
	s_waitcnt lgkmcnt(0)
	v_mfma_f32_16x16x32_bf16 v[98:101], v[152:155], v[82:85], v[98:101]

.LBB0_552:
	v_cvt_pk_bf16_f32 v126, v126, v127
	v_cvt_pk_bf16_f32 v127, v128, v129
	v_cvt_pk_bf16_f32 v128, v122, v123
	v_cvt_pk_bf16_f32 v129, v124, v125
	ds_read_b128 v[152:155], v137 offset:34816
	ds_read_b128 v[156:159], v137 offset:39168
	ds_read_b128 v[160:163], v137 offset:43520
	ds_read_b128 v[164:167], v137 offset:47872
	ds_read_b128 v[168:171], v137 offset:52224
	ds_read_b128 v[172:175], v137 offset:56576
	ds_read_b128 v[176:179], v137 offset:60928
	ds_read_b128 v[180:183], v137 offset:65280
	s_waitcnt lgkmcnt(7)
	v_mfma_f32_16x16x32_bf16 v[78:81], v[152:155], v[126:129], v[78:81]
	s_waitcnt lgkmcnt(6)
	v_mfma_f32_16x16x32_bf16 v[74:77], v[156:159], v[126:129], v[74:77]
	s_waitcnt lgkmcnt(5)
	v_mfma_f32_16x16x32_bf16 v[70:73], v[160:163], v[126:129], v[70:73]
	s_waitcnt lgkmcnt(4)
	v_mfma_f32_16x16x32_bf16 v[66:69], v[164:167], v[126:129], v[66:69]
	s_waitcnt lgkmcnt(3)
	v_mfma_f32_16x16x32_bf16 v[46:49], v[168:171], v[126:129], v[46:49]
	s_waitcnt lgkmcnt(2)
	v_mfma_f32_16x16x32_bf16 v[42:45], v[172:175], v[126:129], v[42:45]
	s_waitcnt lgkmcnt(1)
	v_mfma_f32_16x16x32_bf16 v[38:41], v[176:179], v[126:129], v[38:41]
	s_waitcnt lgkmcnt(0)
	v_mfma_f32_16x16x32_bf16 v[34:37], v[180:183], v[126:129], v[34:37]
	s_or_b64 s[12:13], s[84:85], s[76:77]
	s_and_b64 vcc, exec, s[12:13]
	s_cbranch_vccnz .LBB0_542
.LBB0_553:
	v_cvt_pk_bf16_f32 v118, v118, v119
	v_cvt_pk_bf16_f32 v119, v120, v121
	v_cvt_pk_bf16_f32 v120, v114, v115
	v_cvt_pk_bf16_f32 v121, v116, v117
	ds_read_b128 v[152:155], v137 offset:34880
	ds_read_b128 v[156:159], v137 offset:39232
	ds_read_b128 v[160:163], v137 offset:43584
	ds_read_b128 v[164:167], v137 offset:47936
	ds_read_b128 v[168:171], v137 offset:52288
	ds_read_b128 v[172:175], v137 offset:56640
	ds_read_b128 v[176:179], v137 offset:60992
	ds_read_b128 v[180:183], v137 offset:65344
	s_waitcnt lgkmcnt(7)
	v_mfma_f32_16x16x32_bf16 v[78:81], v[152:155], v[118:121], v[78:81]
	s_waitcnt lgkmcnt(6)
	v_mfma_f32_16x16x32_bf16 v[74:77], v[156:159], v[118:121], v[74:77]
	s_waitcnt lgkmcnt(5)
	v_mfma_f32_16x16x32_bf16 v[70:73], v[160:163], v[118:121], v[70:73]
	s_waitcnt lgkmcnt(4)
	v_mfma_f32_16x16x32_bf16 v[66:69], v[164:167], v[118:121], v[66:69]
	s_waitcnt lgkmcnt(3)
	v_mfma_f32_16x16x32_bf16 v[46:49], v[168:171], v[118:121], v[46:49]
	s_waitcnt lgkmcnt(2)
	v_mfma_f32_16x16x32_bf16 v[42:45], v[172:175], v[118:121], v[42:45]
	s_waitcnt lgkmcnt(1)
	v_mfma_f32_16x16x32_bf16 v[38:41], v[176:179], v[118:121], v[38:41]
	s_waitcnt lgkmcnt(0)
	v_mfma_f32_16x16x32_bf16 v[34:37], v[180:183], v[118:121], v[34:37]
	s_or_b64 s[12:13], s[82:83], s[74:75]
	s_and_b64 vcc, exec, s[12:13]
	s_cbranch_vccnz .LBB0_543
.LBB0_554:
	v_cvt_pk_bf16_f32 v110, v110, v111
	v_cvt_pk_bf16_f32 v111, v112, v113
	v_cvt_pk_bf16_f32 v112, v106, v107
	v_cvt_pk_bf16_f32 v113, v108, v109
	ds_read_b128 v[152:155], v137 offset:34944
	ds_read_b128 v[156:159], v137 offset:39296
	ds_read_b128 v[160:163], v137 offset:43648
	ds_read_b128 v[164:167], v137 offset:48000
	ds_read_b128 v[168:171], v137 offset:52352
	ds_read_b128 v[172:175], v137 offset:56704
	ds_read_b128 v[176:179], v137 offset:61056
	ds_read_b128 v[180:183], v137 offset:65408
	s_waitcnt lgkmcnt(7)
	v_mfma_f32_16x16x32_bf16 v[78:81], v[152:155], v[110:113], v[78:81]
	s_waitcnt lgkmcnt(6)
	v_mfma_f32_16x16x32_bf16 v[74:77], v[156:159], v[110:113], v[74:77]
	s_waitcnt lgkmcnt(5)
	v_mfma_f32_16x16x32_bf16 v[70:73], v[160:163], v[110:113], v[70:73]
	s_waitcnt lgkmcnt(4)
	v_mfma_f32_16x16x32_bf16 v[66:69], v[164:167], v[110:113], v[66:69]
	s_waitcnt lgkmcnt(3)
	v_mfma_f32_16x16x32_bf16 v[46:49], v[168:171], v[110:113], v[46:49]
	s_waitcnt lgkmcnt(2)
	v_mfma_f32_16x16x32_bf16 v[42:45], v[172:175], v[110:113], v[42:45]
	s_waitcnt lgkmcnt(1)
	v_mfma_f32_16x16x32_bf16 v[38:41], v[176:179], v[110:113], v[38:41]
	s_waitcnt lgkmcnt(0)
	v_mfma_f32_16x16x32_bf16 v[34:37], v[180:183], v[110:113], v[34:37]
	s_or_b64 s[12:13], s[78:79], s[72:73]
	s_and_b64 vcc, exec, s[12:13]
	s_cbranch_vccnz .LBB0_544
.LBB0_555:
	v_cvt_pk_bf16_f32 v102, v102, v103
	v_cvt_pk_bf16_f32 v103, v104, v105
	v_cvt_pk_bf16_f32 v104, v98, v99
	v_cvt_pk_bf16_f32 v105, v100, v101
	ds_read_b128 v[152:155], v137 offset:35008
	ds_read_b128 v[156:159], v137 offset:39360
	ds_read_b128 v[160:163], v137 offset:43712
	ds_read_b128 v[164:167], v137 offset:48064
	ds_read_b128 v[168:171], v137 offset:52416
	ds_read_b128 v[172:175], v137 offset:56768
	ds_read_b128 v[176:179], v137 offset:61120
	ds_read_b128 v[180:183], v137 offset:65472
	s_waitcnt lgkmcnt(7)
	v_mfma_f32_16x16x32_bf16 v[78:81], v[152:155], v[102:105], v[78:81]
	s_waitcnt lgkmcnt(6)
	v_mfma_f32_16x16x32_bf16 v[74:77], v[156:159], v[102:105], v[74:77]
	s_waitcnt lgkmcnt(5)
	v_mfma_f32_16x16x32_bf16 v[70:73], v[160:163], v[102:105], v[70:73]
	s_waitcnt lgkmcnt(4)
	v_mfma_f32_16x16x32_bf16 v[66:69], v[164:167], v[102:105], v[66:69]
	s_waitcnt lgkmcnt(3)
	v_mfma_f32_16x16x32_bf16 v[46:49], v[168:171], v[102:105], v[46:49]
	s_waitcnt lgkmcnt(2)
	v_mfma_f32_16x16x32_bf16 v[42:45], v[172:175], v[102:105], v[42:45]
	s_waitcnt lgkmcnt(1)
	v_mfma_f32_16x16x32_bf16 v[38:41], v[176:179], v[102:105], v[38:41]
	s_waitcnt lgkmcnt(0)
	v_mfma_f32_16x16x32_bf16 v[34:37], v[180:183], v[102:105], v[34:37]
	v_add_f32_e32 v98, v143, v145
	s_and_b64 vcc, exec, s[38:39]
	v_fmac_f32_e32 v98, v142, v138
	s_cbranch_vccnz .LBB0_484
